# MLA and NA unit epilogues: eight z loads issued together (one wait), waits on stores dropped
# baseline (speedup 1.0000x reference)
; DEV int opaque_tid() { int t = threadIdx.x; asm volatile("" : "+v"(t)); return t; }
; template <int NV>
; DEV void attn_store(f32x16 (&o)[NV], float scale_lane, const u16* zrow, u16* arow, const float* vgain  ) {
;   const int lane = opaque_tid() & 63, h = lane >> 5;
; #pragma unroll
;   for (int v = 0; v < NV; ++v) {
;     float ov[16];
; #pragma unroll
;     for (int g4 = 0; g4 < 4; ++g4) {
;       const int f = 32 * v + 8 * g4 + 4 * h;
;       const uint2 zz = *(const uint2*)(zrow + f);
;       float z0 = __uint_as_float(zz.x << 16), z1 = __uint_as_float(zz.x & 0xffff0000u);
;       float z2 = __uint_as_float(zz.y << 16), z3 = __uint_as_float(zz.y & 0xffff0000u);
;       float a0 = o[v][4 * g4] * scale_lane, a1 = o[v][4 * g4 + 1] * scale_lane, a2 = o[v][4 * g4 + 2] * scale_lane,
;             a3 = o[v][4 * g4 + 3] * scale_lane;
;       if (vgain) {
;         const float4 gg = *(const float4*)(vgain + f);
;         a0 *= gg.x; a1 *= gg.y; a2 *= gg.z; a3 *= gg.w;
;       }
;       ov[4 * g4] = a0 * z0; ov[4 * g4 + 1] = a1 * z1; ov[4 * g4 + 2] = a2 * z2; ov[4 * g4 + 3] = a3 * z3;
;     }
;     store_row32(arow + 32 * v, ov, h);
; DEV void attn_mla_unit(const Params& p, int bl, int hd, int q_t0, int n_tiles, char* smem) {
;     ...
;   const int tp = q_t0 + w * 32 + r;
;   const size_t m = (size_t)bl * TP + tp;
;   attn_store<2>(o, linv, (const u16*)(ws + OFF_Z) + m * 1536 + 512 + hd * 64, (u16*)(ws + OFF_ACAT) + m * 1536 + 512 + hd * 64, nullptr);
.LBB0_128:
	v_and_b32_e32 v34, 64, v175
	v_xor_b32_e32 v32, 32, v175
	v_add_u32_e32 v34, 64, v34
	v_cmp_lt_i32_e32 vcc, v32, v34
	v_ashrrev_i32_e32 v34, 1, v142
	v_and_b32_e32 v33, 31, v142
	v_and_b32_e32 v34, 0xffffffe0, v34
	v_add3_u32 v34, v33, s17, v34
	s_ashr_i32 s2, s16, 3
	v_ashrrev_i32_e32 v35, 31, v34
	v_mad_i64_i32 v[34:35], s[2:3], s2, v176, v[34:35]
	v_mov_b64_e32 v[36:37], s[0:1]
	v_mad_u64_u32 v[36:37], s[0:1], v34, s47, v[36:37]
	v_mov_b32_e32 v33, v147
	s_barrier
	s_lshl_b32 s0, s16, 7
	v_mad_i32_i24 v37, v35, s47, v37
	s_and_b32 s34, s0, 0x380
	v_bfe_u32 v33, v33, 5, 1
	v_lshl_add_u64 v[36:37], v[36:37], 0, s[34:35]
	v_lshlrev_b32_e32 v144, 4, v33
	v_lshl_add_u64 v[38:39], v[36:37], 0, v[144:145]
	s_mov_b64 s[0:1], 0x1c4d6500
	v_lshlrev_b32_e32 v144, 3, v33
	v_lshl_add_u64 v[34:35], v[38:39], 0, s[0:1]
	v_lshl_add_u64 v[40:41], v[36:37], 0, v[144:145]
	s_mov_b64 s[0:1], 0xee56500
	v_lshl_add_u64 v[36:37], v[40:41], 0, s[0:1]
	s_mov_b32 s0, 0xee56000
	v_cndmask_b32_e32 v32, v175, v32, vcc
	v_add_co_u32_e32 v40, vcc, s0, v40
	v_lshlrev_b32_e32 v32, 2, v32
	s_nop 0
	v_addc_co_u32_e32 v41, vcc, 0, v41, vcc
	global_load_dwordx2 v[200:201], v[36:37], off
	global_load_dwordx2 v[202:203], v[36:37], off offset:16
	global_load_dwordx2 v[204:205], v[36:37], off offset:32
	global_load_dwordx2 v[206:207], v[36:37], off offset:48
	global_load_dwordx2 v[208:209], v[36:37], off offset:64
	global_load_dwordx2 v[210:211], v[36:37], off offset:80
	global_load_dwordx2 v[212:213], v[36:37], off offset:96
	global_load_dwordx2 v[214:215], v[36:37], off offset:112
	ds_bpermute_b32 v32, v32, v134
	s_mov_b32 s0, 0x1c4d6000
	s_waitcnt lgkmcnt(0)
	v_add_f32_e32 v32, v134, v32
	v_rcp_f32_e32 v32, v32
	s_waitcnt vmcnt(0)
	v_lshlrev_b32_e32 v42, 16, v200
	v_and_b32_e32 v43, 0xffff0000, v200
	v_lshlrev_b32_e32 v40, 16, v201
	v_and_b32_e32 v41, 0xffff0000, v201
	v_pk_mul_f32 v[18:19], v[18:19], v[32:33] op_sel_hi:[1,0]
	v_pk_mul_f32 v[16:17], v[16:17], v[32:33] op_sel_hi:[1,0]
	v_pk_mul_f32 v[18:19], v[18:19], v[40:41]
	v_pk_mul_f32 v[16:17], v[16:17], v[42:43]
	v_pk_mul_f32 v[22:23], v[22:23], v[32:33] op_sel_hi:[1,0]
	v_pk_mul_f32 v[20:21], v[20:21], v[32:33] op_sel_hi:[1,0]
	v_pk_mul_f32 v[24:25], v[24:25], v[32:33] op_sel_hi:[1,0]
	v_cvt_pk_bf16_f32 v16, v16, v17
	v_cvt_pk_bf16_f32 v17, v18, v19
	v_pk_mul_f32 v[26:27], v[26:27], v[32:33] op_sel_hi:[1,0]
	v_pk_mul_f32 v[2:3], v[2:3], v[32:33] op_sel_hi:[1,0]
	v_pk_mul_f32 v[0:1], v[0:1], v[32:33] op_sel_hi:[1,0]
	v_pk_mul_f32 v[6:7], v[6:7], v[32:33] op_sel_hi:[1,0]
	v_pk_mul_f32 v[4:5], v[4:5], v[32:33] op_sel_hi:[1,0]
	v_pk_mul_f32 v[10:11], v[10:11], v[32:33] op_sel_hi:[1,0]
	v_pk_mul_f32 v[8:9], v[8:9], v[32:33] op_sel_hi:[1,0]
	v_pk_mul_f32 v[28:29], v[28:29], v[32:33] op_sel_hi:[1,0]
	v_pk_mul_f32 v[30:31], v[30:31], v[32:33] op_sel_hi:[1,0]
	v_pk_mul_f32 v[12:13], v[12:13], v[32:33] op_sel_hi:[1,0]
	v_pk_mul_f32 v[14:15], v[14:15], v[32:33] op_sel_hi:[1,0]
	v_lshlrev_b32_e32 v42, 16, v202
	v_and_b32_e32 v43, 0xffff0000, v202
	v_lshlrev_b32_e32 v40, 16, v203
	v_and_b32_e32 v41, 0xffff0000, v203
	v_pk_mul_f32 v[22:23], v[22:23], v[40:41]
	v_pk_mul_f32 v[20:21], v[20:21], v[42:43]
	v_cvt_pk_bf16_f32 v19, v22, v23
	v_cvt_pk_bf16_f32 v18, v20, v21
	s_nop 1
	v_permlane32_swap_b32_e32 v16, v18
	v_permlane32_swap_b32_e32 v17, v19
	v_lshlrev_b32_e32 v42, 16, v204
	v_and_b32_e32 v43, 0xffff0000, v204
	v_pk_mul_f32 v[24:25], v[24:25], v[42:43]
	v_lshlrev_b32_e32 v40, 16, v205
	v_cvt_pk_bf16_f32 v20, v24, v25
	v_add_co_u32_e32 v24, vcc, s0, v38
	v_and_b32_e32 v41, 0xffff0000, v205
	s_nop 0
	v_addc_co_u32_e32 v25, vcc, 0, v39, vcc
	v_pk_mul_f32 v[26:27], v[26:27], v[40:41]
	v_cvt_pk_bf16_f32 v21, v26, v27
	flat_store_dwordx4 v[24:25], v[16:19] offset:1280
	v_lshlrev_b32_e32 v42, 16, v206
	v_and_b32_e32 v43, 0xffff0000, v206
	v_lshlrev_b32_e32 v40, 16, v207
	v_lshlrev_b32_e32 v18, 16, v208
	v_and_b32_e32 v19, 0xffff0000, v208
	v_lshlrev_b32_e32 v16, 16, v209
	v_and_b32_e32 v17, 0xffff0000, v209
	v_pk_mul_f32 v[2:3], v[2:3], v[16:17]
	v_pk_mul_f32 v[0:1], v[0:1], v[18:19]
	v_and_b32_e32 v41, 0xffff0000, v207
	v_pk_mul_f32 v[28:29], v[28:29], v[42:43]
	v_pk_mul_f32 v[30:31], v[30:31], v[40:41]
	v_cvt_pk_bf16_f32 v22, v28, v29
	v_cvt_pk_bf16_f32 v23, v30, v31
	v_cvt_pk_bf16_f32 v0, v0, v1
	v_cvt_pk_bf16_f32 v1, v2, v3
	v_permlane32_swap_b32_e32 v20, v22
	v_permlane32_swap_b32_e32 v21, v23
	flat_store_dwordx4 v[34:35], v[20:23] offset:32
	v_lshlrev_b32_e32 v18, 16, v210
	v_and_b32_e32 v19, 0xffff0000, v210
	v_lshlrev_b32_e32 v16, 16, v211
	v_and_b32_e32 v17, 0xffff0000, v211
	v_pk_mul_f32 v[6:7], v[6:7], v[16:17]
	v_pk_mul_f32 v[4:5], v[4:5], v[18:19]
	v_cvt_pk_bf16_f32 v3, v6, v7
	v_cvt_pk_bf16_f32 v2, v4, v5
	s_nop 1
	v_permlane32_swap_b32_e32 v0, v2
	v_permlane32_swap_b32_e32 v1, v3
	flat_store_dwordx4 v[34:35], v[0:3] offset:64
	v_lshlrev_b32_e32 v18, 16, v212
	v_and_b32_e32 v19, 0xffff0000, v212
	v_lshlrev_b32_e32 v16, 16, v213
	v_and_b32_e32 v17, 0xffff0000, v213
	v_pk_mul_f32 v[10:11], v[10:11], v[16:17]
	v_pk_mul_f32 v[8:9], v[8:9], v[18:19]
	v_cvt_pk_bf16_f32 v5, v10, v11
	v_cvt_pk_bf16_f32 v4, v8, v9
	v_lshlrev_b32_e32 v18, 16, v214
	v_and_b32_e32 v19, 0xffff0000, v214
	v_lshlrev_b32_e32 v16, 16, v215
	v_and_b32_e32 v17, 0xffff0000, v215
	v_pk_mul_f32 v[12:13], v[12:13], v[18:19]
	v_pk_mul_f32 v[14:15], v[14:15], v[16:17]
	v_cvt_pk_bf16_f32 v6, v12, v13
	v_cvt_pk_bf16_f32 v7, v14, v15
	s_nop 0
	v_permlane32_swap_b32_e32 v4, v6
	v_permlane32_swap_b32_e32 v5, v7
	flat_store_dwordx4 v[34:35], v[4:7] offset:96

; DEV int opaque_tid() { int t = threadIdx.x; asm volatile("" : "+v"(t)); return t; }
; template <int NV>
; DEV void attn_store(f32x16 (&o)[NV], float scale_lane, const u16* zrow, u16* arow, const float* vgain  ) {
;   const int lane = opaque_tid() & 63, h = lane >> 5;
; #pragma unroll
;   for (int v = 0; v < NV; ++v) {
;     float ov[16];
; #pragma unroll
;     for (int g4 = 0; g4 < 4; ++g4) {
;       const int f = 32 * v + 8 * g4 + 4 * h;
;       const uint2 zz = *(const uint2*)(zrow + f);
;       float z0 = __uint_as_float(zz.x << 16), z1 = __uint_as_float(zz.x & 0xffff0000u);
;       float z2 = __uint_as_float(zz.y << 16), z3 = __uint_as_float(zz.y & 0xffff0000u);
;       float a0 = o[v][4 * g4] * scale_lane, a1 = o[v][4 * g4 + 1] * scale_lane, a2 = o[v][4 * g4 + 2] * scale_lane,
;             a3 = o[v][4 * g4 + 3] * scale_lane;
;       if (vgain) {
;         const float4 gg = *(const float4*)(vgain + f);
;         a0 *= gg.x; a1 *= gg.y; a2 *= gg.z; a3 *= gg.w;
;       }
;       ov[4 * g4] = a0 * z0; ov[4 * g4 + 1] = a1 * z1; ov[4 * g4 + 2] = a2 * z2; ov[4 * g4 + 3] = a3 * z3;
;     }
;     store_row32(arow + 32 * v, ov, h);
; DEV void attn_na_unit(const Params& p, int l, int bl, int hd, int qb, char* smem) {
;     ...
;   const int tp = fa.q_t0 + w * 32 + r;
;   const size_t m = (size_t)bl * TP + tp;
;   attn_store<2>(o, linv, (const u16*)(ws + OFF_Z) + m * 1536 + hd * 64, (u16*)(ws + OFF_ACAT) + m * 1536 + hd * 64, nullptr);
.LBB0_202:
	v_and_b32_e32 v33, 64, v175
	v_xor_b32_e32 v32, 32, v175
	v_add_u32_e32 v33, 64, v33
	v_cmp_lt_i32_e32 vcc, v32, v33
	v_ashrrev_i32_e32 v33, 1, v132
	s_movk_i32 s1, 0xffe0
	v_bfi_b32 v33, s1, v33, v132
	v_add_u32_e32 v34, s30, v33
	s_ashr_i32 s0, s92, 3
	v_ashrrev_i32_e32 v35, 31, v34
	v_mad_i64_i32 v[34:35], s[0:1], s0, v176, v[34:35]
	v_readlane_b32 s0, v240, 7
	v_readlane_b32 s1, v240, 8
	v_mov_b64_e32 v[36:37], s[84:85]
	s_movk_i32 s2, 0xc00
	v_mov_b32_e32 v33, v147
	s_barrier
	s_mov_b32 s5, s1
	v_mad_u64_u32 v[36:37], s[0:1], v34, s2, v[36:37]
	s_lshl_b32 s4, s31, 7
	v_mad_i32_i24 v37, v35, s2, v37
	s_mov_b32 s1, s5
	v_bfe_u32 v33, v33, 5, 1
	v_writelane_b32 v240, s0, 7
	v_lshl_add_u64 v[36:37], v[36:37], 0, s[4:5]
	v_lshlrev_b32_e32 v144, 4, v33
	v_writelane_b32 v240, s1, 8
	v_lshl_add_u64 v[38:39], v[36:37], 0, v[144:145]
	s_mov_b64 s[0:1], 0x1c4d6100
	v_lshlrev_b32_e32 v144, 3, v33
	v_lshl_add_u64 v[34:35], v[38:39], 0, s[0:1]
	v_lshl_add_u64 v[40:41], v[36:37], 0, v[144:145]
	s_mov_b64 s[0:1], 0xee56100
	v_lshl_add_u64 v[36:37], v[40:41], 0, s[0:1]
	s_mov_b32 s0, 0xee56000
	v_cndmask_b32_e32 v32, v175, v32, vcc
	v_add_co_u32_e32 v40, vcc, s0, v40
	v_lshlrev_b32_e32 v32, 2, v32
	s_nop 0
	v_addc_co_u32_e32 v41, vcc, 0, v41, vcc
	s_waitcnt vmcnt(0)
	global_load_dwordx2 v[200:201], v[36:37], off
	global_load_dwordx2 v[202:203], v[36:37], off offset:16
	global_load_dwordx2 v[204:205], v[36:37], off offset:32
	global_load_dwordx2 v[206:207], v[36:37], off offset:48
	global_load_dwordx2 v[208:209], v[36:37], off offset:64
	global_load_dwordx2 v[210:211], v[36:37], off offset:80
	global_load_dwordx2 v[212:213], v[36:37], off offset:96
	global_load_dwordx2 v[214:215], v[36:37], off offset:112
	ds_bpermute_b32 v32, v32, v142
	s_mov_b32 s0, 0x1c4d6000
	s_movk_i32 s80, 0xc00
	v_readlane_b32 s50, v240, 27
	v_readlane_b32 s51, v240, 28
	s_waitcnt lgkmcnt(0)
	v_add_f32_e32 v32, v142, v32
	v_rcp_f32_e32 v32, v32
	s_waitcnt vmcnt(0)
	v_lshlrev_b32_e32 v42, 16, v200
	v_and_b32_e32 v43, 0xffff0000, v200
	v_lshlrev_b32_e32 v40, 16, v201
	v_and_b32_e32 v41, 0xffff0000, v201
	v_pk_mul_f32 v[18:19], v[18:19], v[32:33] op_sel_hi:[1,0]
	v_pk_mul_f32 v[16:17], v[16:17], v[32:33] op_sel_hi:[1,0]
	v_pk_mul_f32 v[18:19], v[18:19], v[40:41]
	v_pk_mul_f32 v[16:17], v[16:17], v[42:43]
	v_pk_mul_f32 v[22:23], v[22:23], v[32:33] op_sel_hi:[1,0]
	v_pk_mul_f32 v[20:21], v[20:21], v[32:33] op_sel_hi:[1,0]
	v_pk_mul_f32 v[24:25], v[24:25], v[32:33] op_sel_hi:[1,0]
	v_cvt_pk_bf16_f32 v16, v16, v17
	v_cvt_pk_bf16_f32 v17, v18, v19
	v_pk_mul_f32 v[26:27], v[26:27], v[32:33] op_sel_hi:[1,0]
	v_pk_mul_f32 v[2:3], v[2:3], v[32:33] op_sel_hi:[1,0]
	v_pk_mul_f32 v[0:1], v[0:1], v[32:33] op_sel_hi:[1,0]
	v_pk_mul_f32 v[6:7], v[6:7], v[32:33] op_sel_hi:[1,0]
	v_pk_mul_f32 v[4:5], v[4:5], v[32:33] op_sel_hi:[1,0]
	v_pk_mul_f32 v[10:11], v[10:11], v[32:33] op_sel_hi:[1,0]
	v_pk_mul_f32 v[8:9], v[8:9], v[32:33] op_sel_hi:[1,0]
	v_pk_mul_f32 v[28:29], v[28:29], v[32:33] op_sel_hi:[1,0]
	v_pk_mul_f32 v[30:31], v[30:31], v[32:33] op_sel_hi:[1,0]
	v_pk_mul_f32 v[12:13], v[12:13], v[32:33] op_sel_hi:[1,0]
	v_pk_mul_f32 v[14:15], v[14:15], v[32:33] op_sel_hi:[1,0]
	v_lshlrev_b32_e32 v42, 16, v202
	v_and_b32_e32 v43, 0xffff0000, v202
	v_lshlrev_b32_e32 v40, 16, v203
	v_and_b32_e32 v41, 0xffff0000, v203
	v_pk_mul_f32 v[22:23], v[22:23], v[40:41]
	v_pk_mul_f32 v[20:21], v[20:21], v[42:43]
	v_cvt_pk_bf16_f32 v19, v22, v23
	v_cvt_pk_bf16_f32 v18, v20, v21
	s_nop 1
	v_permlane32_swap_b32_e32 v16, v18
	v_permlane32_swap_b32_e32 v17, v19
	v_lshlrev_b32_e32 v42, 16, v204
	v_and_b32_e32 v43, 0xffff0000, v204
	v_pk_mul_f32 v[24:25], v[24:25], v[42:43]
	v_lshlrev_b32_e32 v40, 16, v205
	v_cvt_pk_bf16_f32 v20, v24, v25
	v_add_co_u32_e32 v24, vcc, s0, v38
	v_and_b32_e32 v41, 0xffff0000, v205
	s_nop 0
	v_addc_co_u32_e32 v25, vcc, 0, v39, vcc
	v_pk_mul_f32 v[26:27], v[26:27], v[40:41]
	v_cvt_pk_bf16_f32 v21, v26, v27
	flat_store_dwordx4 v[24:25], v[16:19] offset:256
	v_lshlrev_b32_e32 v42, 16, v206
	v_and_b32_e32 v43, 0xffff0000, v206
	v_lshlrev_b32_e32 v40, 16, v207
	v_lshlrev_b32_e32 v18, 16, v208
	v_and_b32_e32 v19, 0xffff0000, v208
	v_lshlrev_b32_e32 v16, 16, v209
	v_and_b32_e32 v17, 0xffff0000, v209
	v_pk_mul_f32 v[2:3], v[2:3], v[16:17]
	v_pk_mul_f32 v[0:1], v[0:1], v[18:19]
	v_and_b32_e32 v41, 0xffff0000, v207
	v_pk_mul_f32 v[28:29], v[28:29], v[42:43]
	v_pk_mul_f32 v[30:31], v[30:31], v[40:41]
	v_cvt_pk_bf16_f32 v22, v28, v29
	v_cvt_pk_bf16_f32 v23, v30, v31
	v_cvt_pk_bf16_f32 v0, v0, v1
	v_cvt_pk_bf16_f32 v1, v2, v3
	v_permlane32_swap_b32_e32 v20, v22
	v_permlane32_swap_b32_e32 v21, v23
	flat_store_dwordx4 v[34:35], v[20:23] offset:32
	v_lshlrev_b32_e32 v18, 16, v210
	v_and_b32_e32 v19, 0xffff0000, v210
	v_lshlrev_b32_e32 v16, 16, v211
	v_and_b32_e32 v17, 0xffff0000, v211
	v_pk_mul_f32 v[6:7], v[6:7], v[16:17]
	v_pk_mul_f32 v[4:5], v[4:5], v[18:19]
	v_cvt_pk_bf16_f32 v3, v6, v7
	v_cvt_pk_bf16_f32 v2, v4, v5
	s_nop 1
	v_permlane32_swap_b32_e32 v0, v2
	v_permlane32_swap_b32_e32 v1, v3
	flat_store_dwordx4 v[34:35], v[0:3] offset:64
	v_lshlrev_b32_e32 v18, 16, v212
	v_and_b32_e32 v19, 0xffff0000, v212
	v_lshlrev_b32_e32 v16, 16, v213
	v_and_b32_e32 v17, 0xffff0000, v213
	v_pk_mul_f32 v[10:11], v[10:11], v[16:17]
	v_pk_mul_f32 v[8:9], v[8:9], v[18:19]
	v_cvt_pk_bf16_f32 v5, v10, v11
	v_cvt_pk_bf16_f32 v4, v8, v9
	v_lshlrev_b32_e32 v18, 16, v214
	v_and_b32_e32 v19, 0xffff0000, v214
	v_lshlrev_b32_e32 v16, 16, v215
	v_and_b32_e32 v17, 0xffff0000, v215
	v_pk_mul_f32 v[12:13], v[12:13], v[18:19]
	v_pk_mul_f32 v[14:15], v[14:15], v[16:17]
	v_cvt_pk_bf16_f32 v6, v12, v13
	v_cvt_pk_bf16_f32 v7, v14, v15
	s_nop 0
	v_permlane32_swap_b32_e32 v4, v6
	v_permlane32_swap_b32_e32 v5, v7
	flat_store_dwordx4 v[34:35], v[4:7] offset:96
